# prologue weight transpose: 16 norm-gain loads issued together (were load-wait-multiply one by one)
# baseline (speedup 1.0000x reference)
; #define LAS __attribute__((address_space(3)))
; template <int MAP> __device__ __forceinline__ void transpose_item(const float* W, int K, int Nsrc, bf16_t* WT, int nblk, int item, LAS float* scr, int lane, const float* gain = nullptr) {
;     const int kb = item / nblk, nb = item % nblk, k0 = 64 * kb, n0 = 64 * nb;
;     const int nl = 4 * (lane & 15), kr = lane >> 4;
;     const int ns = src_col<MAP>(n0 + nl);
;     f32x4 v[16];
; #pragma unroll
;     for (int i = 0; i < 16; ++i) v[i] = (ns >= 0) ? *(const f32x4*)(W + (size_t)(k0 + kr + 4 * i) * Nsrc + ns) : (f32x4){0.f, 0.f, 0.f, 0.f};
;     if (gain) {
; #pragma unroll
;         for (int i = 0; i < 16; ++i) v[i] = v[i] * gain[k0 + kr + 4 * i];
;     }
; #pragma unroll
;     for (int i = 0; i < 16; ++i) { LAS float* d = scr + (kr + 4 * i) * TP + nl; d[0] = v[i][0]; d[1] = v[i][1]; d[2] = v[i][2]; d[3] = v[i][3]; }
.LBB0_42:
	s_andn2_b64 vcc, exec, s[42:43]
	s_cbranch_vccnz .LBB0_46
	s_movk_i32 s6, 0x90
	s_ashr_i32 s43, s6, 31
	s_add_u32 s42, s0, s6
	s_addc_u32 s43, s1, s43
	s_load_dwordx2 s[42:43], s[42:43], 0x0
	s_mov_b32 s6, 32
	v_mov_b32_e32 v5, v2
	v_mov_b32_e32 v59, v2
	s_waitcnt lgkmcnt(0)
	s_add_u32 s46, s42, s83
	s_addc_u32 s47, s43, s82
	s_ashr_i32 s43, s6, 31
	s_add_u32 s42, s0, s6
	s_addc_u32 s43, s1, s43
	s_add_i32 s6, s86, 0xfc80
	s_and_b32 s44, s6, 0xffff
	s_mul_i32 s44, s44, 0xba2f
	s_lshr_b32 s45, s44, 16
	s_lshr_b32 s44, s44, 22
	s_mulk_i32 s44, 0x58
	s_sub_i32 s48, s6, s44
	s_and_b32 s6, s45, 0xffc0
	s_lshl_b32 s45, s48, 6
	s_and_b32 s44, s45, 0xffc0
	s_and_b32 s45, s45, 0xc0
	s_cmpk_lt_u32 s45, 0x80
	v_or_b32_e32 v3, s45, v72
	s_cselect_b64 vcc, -1, 0
	s_lshl_b32 s45, s48, 5
	s_and_b32 s45, s45, 0xf80
	v_or_b32_e32 v4, s45, v3
	v_add_u32_e32 v3, s45, v3
	v_add_u32_e32 v3, 0xa80, v3
	v_cndmask_b32_e32 v4, v3, v4, vcc
	v_or_b32_e32 v3, s6, v71
	v_lshlrev_b32_e32 v4, 2, v4
	v_lshl_add_u64 v[56:57], s[46:47], 0, v[4:5]
	v_mul_u32_u24_e32 v4, 0x1600, v3
	v_lshlrev_b32_e32 v58, 2, v4
	v_lshl_add_u64 v[12:13], v[56:57], 0, v[58:59]
	v_add_co_u32_e32 v8, vcc, s74, v12
	v_add_u32_e32 v14, 0x42000, v58
	s_nop 0
	v_addc_co_u32_e32 v9, vcc, 0, v13, vcc
	global_load_dwordx4 v[4:7], v[12:13], off
	s_nop 0
	global_load_dwordx4 v[8:11], v[8:9], off
	v_add_co_u32_e32 v12, vcc, s69, v12
	v_mov_b32_e32 v15, v2
	v_add_u32_e32 v20, 0x58000, v58
	v_mov_b32_e32 v21, v2
	v_add_u32_e32 v22, 0x6e000, v58
	v_mov_b32_e32 v23, v2
	v_add_u32_e32 v28, 0x84000, v58
	v_mov_b32_e32 v29, v2
	v_add_u32_e32 v30, 0x9a000, v58
	v_mov_b32_e32 v31, v2
	v_add_u32_e32 v32, 0xb0000, v58
	v_mov_b32_e32 v33, v2
	v_add_u32_e32 v34, 0xc6000, v58
	v_mov_b32_e32 v35, v2
	v_add_u32_e32 v40, 0xdc000, v58
	v_mov_b32_e32 v41, v2
	v_add_u32_e32 v42, 0xf2000, v58
	v_mov_b32_e32 v43, v2
	v_add_u32_e32 v48, 0x108000, v58
	v_mov_b32_e32 v49, v2
	v_add_u32_e32 v50, 0x11e000, v58
	v_mov_b32_e32 v51, v2
	v_add_u32_e32 v64, 0x134000, v58
	v_mov_b32_e32 v65, v2
	v_add_u32_e32 v58, 0x14a000, v58
	v_addc_co_u32_e32 v13, vcc, 0, v13, vcc
	v_lshl_add_u64 v[14:15], v[56:57], 0, v[14:15]
	v_lshl_add_u64 v[20:21], v[56:57], 0, v[20:21]
	v_lshl_add_u64 v[22:23], v[56:57], 0, v[22:23]
	v_lshl_add_u64 v[28:29], v[56:57], 0, v[28:29]
	v_lshl_add_u64 v[30:31], v[56:57], 0, v[30:31]
	v_lshl_add_u64 v[32:33], v[56:57], 0, v[32:33]
	v_lshl_add_u64 v[34:35], v[56:57], 0, v[34:35]
	v_lshl_add_u64 v[40:41], v[56:57], 0, v[40:41]
	v_lshl_add_u64 v[42:43], v[56:57], 0, v[42:43]
	v_lshl_add_u64 v[48:49], v[56:57], 0, v[48:49]
	v_lshl_add_u64 v[50:51], v[56:57], 0, v[50:51]
	v_lshl_add_u64 v[64:65], v[56:57], 0, v[64:65]
	v_lshl_add_u64 v[56:57], v[56:57], 0, v[58:59]
	global_load_dwordx4 v[16:19], v[12:13], off
	s_nop 0
	global_load_dwordx4 v[12:15], v[14:15], off
	s_nop 0
	global_load_dwordx4 v[24:27], v[20:21], off
	s_nop 0
	global_load_dwordx4 v[20:23], v[22:23], off
	s_nop 0
	global_load_dwordx4 v[36:39], v[28:29], off
	s_nop 0
	global_load_dwordx4 v[28:31], v[30:31], off
	s_nop 0
	global_load_dwordx4 v[44:47], v[32:33], off
	s_nop 0
	global_load_dwordx4 v[32:35], v[34:35], off
	s_nop 0
	global_load_dwordx4 v[52:55], v[40:41], off
	s_nop 0
	global_load_dwordx4 v[40:43], v[42:43], off
	s_nop 0
	global_load_dwordx4 v[60:63], v[48:49], off
	s_nop 0
	global_load_dwordx4 v[48:51], v[50:51], off
	s_nop 0
	global_load_dwordx4 v[64:67], v[64:65], off
	s_nop 0
	global_load_dwordx4 v[56:59], v[56:57], off
	s_load_dwordx2 s[42:43], s[42:43], 0x0
	s_waitcnt lgkmcnt(0)
	s_cmp_eq_u64 s[42:43], 0
	s_cbranch_scc1 .LBB0_45
	s_lshl_b64 s[46:47], s[38:39], 2
	s_add_u32 s42, s42, s46
	s_addc_u32 s43, s43, s47
	v_lshlrev_b32_e32 v3, 2, v3
	global_load_dword v160, v3, s[42:43]
	global_load_dword v161, v3, s[42:43] offset:16
	global_load_dword v162, v3, s[42:43] offset:32
	global_load_dword v163, v3, s[42:43] offset:48
	global_load_dword v164, v3, s[42:43] offset:64
	global_load_dword v165, v3, s[42:43] offset:80
	global_load_dword v166, v3, s[42:43] offset:96
	global_load_dword v167, v3, s[42:43] offset:112
	global_load_dword v168, v3, s[42:43] offset:128
	global_load_dword v169, v3, s[42:43] offset:144
	global_load_dword v170, v3, s[42:43] offset:160
	global_load_dword v171, v3, s[42:43] offset:176
	global_load_dword v172, v3, s[42:43] offset:192
	global_load_dword v173, v3, s[42:43] offset:208
	global_load_dword v174, v3, s[42:43] offset:224
	global_load_dword v175, v3, s[42:43] offset:240
	s_waitcnt vmcnt(0)
	v_pk_mul_f32 v[6:7], v[6:7], v[160:161] op_sel_hi:[1,0]
	v_pk_mul_f32 v[4:5], v[4:5], v[160:161] op_sel_hi:[1,0]
	v_pk_mul_f32 v[10:11], v[10:11], v[160:161] op_sel:[0,1]
	v_pk_mul_f32 v[8:9], v[8:9], v[160:161] op_sel:[0,1]
	v_pk_mul_f32 v[18:19], v[18:19], v[162:163] op_sel_hi:[1,0]
	v_pk_mul_f32 v[16:17], v[16:17], v[162:163] op_sel_hi:[1,0]
	v_pk_mul_f32 v[14:15], v[14:15], v[162:163] op_sel:[0,1]
	v_pk_mul_f32 v[12:13], v[12:13], v[162:163] op_sel:[0,1]
	v_pk_mul_f32 v[26:27], v[26:27], v[164:165] op_sel_hi:[1,0]
	v_pk_mul_f32 v[24:25], v[24:25], v[164:165] op_sel_hi:[1,0]
	v_pk_mul_f32 v[22:23], v[22:23], v[164:165] op_sel:[0,1]
	v_pk_mul_f32 v[20:21], v[20:21], v[164:165] op_sel:[0,1]
	v_pk_mul_f32 v[38:39], v[38:39], v[166:167] op_sel_hi:[1,0]
	v_pk_mul_f32 v[36:37], v[36:37], v[166:167] op_sel_hi:[1,0]
	v_pk_mul_f32 v[30:31], v[30:31], v[166:167] op_sel:[0,1]
	v_pk_mul_f32 v[28:29], v[28:29], v[166:167] op_sel:[0,1]
	v_pk_mul_f32 v[46:47], v[46:47], v[168:169] op_sel_hi:[1,0]
	v_pk_mul_f32 v[44:45], v[44:45], v[168:169] op_sel_hi:[1,0]
	v_pk_mul_f32 v[34:35], v[34:35], v[168:169] op_sel:[0,1]
	v_pk_mul_f32 v[32:33], v[32:33], v[168:169] op_sel:[0,1]
	v_pk_mul_f32 v[54:55], v[54:55], v[170:171] op_sel_hi:[1,0]
	v_pk_mul_f32 v[52:53], v[52:53], v[170:171] op_sel_hi:[1,0]
	v_pk_mul_f32 v[42:43], v[42:43], v[170:171] op_sel:[0,1]
	v_pk_mul_f32 v[40:41], v[40:41], v[170:171] op_sel:[0,1]
	v_pk_mul_f32 v[62:63], v[62:63], v[172:173] op_sel_hi:[1,0]
	v_pk_mul_f32 v[60:61], v[60:61], v[172:173] op_sel_hi:[1,0]
	v_pk_mul_f32 v[50:51], v[50:51], v[172:173] op_sel:[0,1]
	v_pk_mul_f32 v[48:49], v[48:49], v[172:173] op_sel:[0,1]
	v_pk_mul_f32 v[66:67], v[66:67], v[174:175] op_sel_hi:[1,0]
	v_pk_mul_f32 v[64:65], v[64:65], v[174:175] op_sel_hi:[1,0]
	v_pk_mul_f32 v[58:59], v[58:59], v[174:175] op_sel:[0,1]
	v_pk_mul_f32 v[56:57], v[56:57], v[174:175] op_sel:[0,1]
